# E22: grid barrier L1 invalidate issued by wave 1 at barrier entry (off thread 0's atomic/poll chain), on E20
# baseline (speedup 1.0000x reference)
.LBB0_111:
	s_waitcnt vmcnt(0) lgkmcnt(0)
	s_barrier

.LBB0_1272:
	s_mul_i32 s0, s15, 9
	s_add_i32 s2, s0, 2
	v_readlane_b32 s0, v252, 2
	v_readlane_b32 s1, v252, 3
	s_cmp_lt_i32 s2, s1
	s_cselect_b64 s[0:1], -1, 0
	s_and_b64 s[4:5], s[26:27], s[0:1]
	s_andn2_b64 vcc, exec, s[4:5]
	s_cbranch_vccnz .LBB0_1326
	s_waitcnt vmcnt(0)
	v_readlane_b32 s4, v252, 18
	v_readlane_b32 s5, v252, 19
	s_andn2_b64 vcc, exec, s[4:5]
	s_barrier
	v_readlane_b32 s100, v252, 6
	s_nop 0
	s_cmp_lg_u32 s100, 1
	s_cbranch_scc1 .Lmy_inv_skip1
	buffer_inv sc1
.Lmy_inv_skip1:
	s_cbranch_vccnz .LBB0_1325
	v_mbcnt_lo_u32_b32 v0, -1, 0
	v_mbcnt_hi_u32_b32 v0, -1, v0
	s_nop 0
	v_cmp_eq_u32_e32 vcc, 0, v0
	s_and_saveexec_b64 s[4:5], vcc
	s_cbranch_execz .LBB0_1324
	v_readlane_b32 s6, v255, 0
	s_waitcnt vmcnt(0) expcnt(0) lgkmcnt(0)
	s_nop 0
	v_mov_b32_e32 v0, s6
	ds_read_b32 v2, v0
	v_readlane_b32 s6, v255, 1
	s_waitcnt lgkmcnt(0)
	v_cmp_ne_u32_e32 vcc, 0, v2
	v_mov_b32_e32 v0, s6
	ds_read_b32 v0, v0
	s_cbranch_vccnz .LBB0_1290
	v_readlane_b32 s8, v252, 8
	v_readlane_b32 s9, v252, 9
	s_load_dwordx2 s[6:7], s[8:9], 0x0
	s_nop 0
	s_load_dword s8, s[8:9], 0x8
	s_mov_b32 s13, 1
	s_waitcnt lgkmcnt(0)
	s_mul_i32 s12, s7, s6
	s_mul_i32 s12, s12, s8
	s_branch .LBB0_1278

.LBB0_1292:
	s_or_b64 exec, exec, s[6:7]
	v_cvt_f32_u32_e32 v5, v2
	s_waitcnt vmcnt(0)
	v_readfirstlane_b32 s6, v4
	v_sub_u32_e32 v4, 0, v2
	v_rcp_iflag_f32_e32 v5, v5
	v_add_u32_e32 v6, s6, v1
	v_mul_f32_e32 v5, 0x4f7ffffe, v5
	v_cvt_u32_f32_e32 v5, v5
	v_mul_lo_u32 v1, v4, v5
	v_mul_hi_u32 v1, v5, v1
	v_add_u32_e32 v1, v5, v1
	v_mul_hi_u32 v1, v6, v1
	v_mul_lo_u32 v4, v1, v2
	v_sub_u32_e32 v4, v6, v4
	v_add_u32_e32 v5, 1, v1
	v_cmp_ge_u32_e32 vcc, v4, v2
	s_nop 1
	v_cndmask_b32_e32 v1, v1, v5, vcc
	v_sub_u32_e32 v5, v4, v2
	v_cndmask_b32_e32 v4, v4, v5, vcc
	v_add_u32_e32 v5, 1, v1
	v_cmp_ge_u32_e32 vcc, v4, v2
	v_add_u32_e32 v4, 1, v6
	s_nop 0
	v_cndmask_b32_e32 v1, v1, v5, vcc
	v_mul_lo_u32 v5, v2, v1
	v_add_u32_e32 v2, v5, v2
	v_cmp_ne_u32_e32 vcc, v4, v2
	s_and_saveexec_b64 s[6:7], vcc
	s_xor_b64 s[6:7], exec, s[6:7]
	s_cbranch_execz .LBB0_1306
	v_readlane_b32 s8, v253, 26
	v_readlane_b32 s9, v253, 27
	s_waitcnt lgkmcnt(0)
	v_add_u32_e32 v1, 1, v1
	v_mul_lo_u32 v1, v1, v0
	s_nop 2
	global_load_dword v0, v3, s[8:9] sc1
	s_waitcnt vmcnt(0)
	v_cmp_lt_u32_e32 vcc, v0, v1
	s_and_saveexec_b64 s[8:9], vcc
	s_cbranch_execz .LBB0_1305
	s_mov_b32 s21, s15
	s_mov_b32 s20, 1
	s_mov_b64 s[10:11], 0
	s_branch .LBB0_1296

.LBB0_1306:
	s_andn2_saveexec_b64 s[6:7], s[6:7]
	s_cbranch_execz .LBB0_1324
	s_mov_b64 s[6:7], exec
	buffer_wbl2 sc1
	s_waitcnt vmcnt(0) lgkmcnt(0)
	s_waitcnt vmcnt(0)
	v_mbcnt_lo_u32_b32 v1, s6, 0
	v_mbcnt_hi_u32_b32 v1, s7, v1
	v_cmp_eq_u32_e32 vcc, 0, v1
	s_and_saveexec_b64 s[8:9], vcc
	s_cbranch_execz .LBB0_1309
	s_bcnt1_i32_b64 s6, s[6:7]
	v_mov_b32_e32 v2, s6
	v_readlane_b32 s6, v253, 26
	v_readlane_b32 s7, v253, 27
	s_nop 4
	global_atomic_add v2, v3, v2, s[6:7] sc0

.LBB0_1394:
	s_mul_i32 s0, s15, 9
	s_add_i32 s2, s0, 3
	v_readlane_b32 s0, v252, 2
	v_readlane_b32 s1, v252, 3
	s_cmp_lt_i32 s2, s1
	v_readlane_b32 s4, v255, 39
	s_cselect_b64 s[0:1], -1, 0
	v_readlane_b32 s5, v255, 40
	s_and_b64 s[4:5], s[4:5], s[0:1]
	s_andn2_b64 vcc, exec, s[4:5]
	s_cbranch_vccnz .LBB0_1448
	s_waitcnt vmcnt(0)
	v_readlane_b32 s4, v252, 18
	v_readlane_b32 s5, v252, 19
	s_andn2_b64 vcc, exec, s[4:5]
	s_barrier
	v_readlane_b32 s100, v252, 6
	s_nop 0
	s_cmp_lg_u32 s100, 1
	s_cbranch_scc1 .Lmy_inv_skip2
	buffer_inv sc1

.LBB0_1463:
	v_readlane_b32 s0, v255, 9
	s_add_i32 s2, s0, 4
	v_readlane_b32 s0, v252, 2
	v_readlane_b32 s1, v252, 3
	s_cmp_lt_i32 s2, s1
	s_cselect_b64 s[0:1], -1, 0
	s_waitcnt lgkmcnt(0)
	s_and_b64 s[4:5], s[8:9], s[0:1]
	s_andn2_b64 vcc, exec, s[4:5]
	s_cbranch_vccnz .LBB0_1517
	s_waitcnt vmcnt(0)
	v_readlane_b32 s4, v252, 18
	v_readlane_b32 s5, v252, 19
	s_andn2_b64 vcc, exec, s[4:5]
	s_barrier
	v_readlane_b32 s100, v252, 6
	s_nop 0
	s_cmp_lg_u32 s100, 1
	s_cbranch_scc1 .Lmy_inv_skip3
	buffer_inv sc1

.LBB0_1483:
	s_or_b64 exec, exec, s[6:7]
	v_cvt_f32_u32_e32 v5, v2
	s_waitcnt vmcnt(0)
	v_readfirstlane_b32 s6, v4
	v_sub_u32_e32 v4, 0, v2
	v_rcp_iflag_f32_e32 v5, v5
	v_add_u32_e32 v6, s6, v1
	v_mul_f32_e32 v5, 0x4f7ffffe, v5
	v_cvt_u32_f32_e32 v5, v5
	v_mul_lo_u32 v1, v4, v5
	v_mul_hi_u32 v1, v5, v1
	v_add_u32_e32 v1, v5, v1
	v_mul_hi_u32 v1, v6, v1
	v_mul_lo_u32 v4, v1, v2
	v_sub_u32_e32 v4, v6, v4
	v_add_u32_e32 v5, 1, v1
	v_cmp_ge_u32_e32 vcc, v4, v2
	s_nop 1
	v_cndmask_b32_e32 v1, v1, v5, vcc
	v_sub_u32_e32 v5, v4, v2
	v_cndmask_b32_e32 v4, v4, v5, vcc
	v_add_u32_e32 v5, 1, v1
	v_cmp_ge_u32_e32 vcc, v4, v2
	v_add_u32_e32 v4, 1, v6
	s_nop 0
	v_cndmask_b32_e32 v1, v1, v5, vcc
	v_mul_lo_u32 v5, v2, v1
	v_add_u32_e32 v2, v5, v2
	v_cmp_ne_u32_e32 vcc, v4, v2
	s_and_saveexec_b64 s[6:7], vcc
	s_xor_b64 s[6:7], exec, s[6:7]
	s_cbranch_execz .LBB0_1497
	v_readlane_b32 s8, v253, 26
	v_readlane_b32 s9, v253, 27
	s_waitcnt lgkmcnt(0)
	v_add_u32_e32 v1, 1, v1
	v_mul_lo_u32 v1, v1, v0
	s_nop 2
	global_load_dword v0, v3, s[8:9] sc1
	s_waitcnt vmcnt(0)
	v_cmp_lt_u32_e32 vcc, v0, v1
	s_and_saveexec_b64 s[8:9], vcc
	s_cbranch_execz .LBB0_1496
	s_mov_b32 s20, 1
	s_mov_b64 s[10:11], 0
	s_branch .LBB0_1487

.LBB0_1577:
	v_readlane_b32 s2, v255, 9
	v_readlane_b32 s4, v252, 2
	s_add_i32 s2, s2, 6
	v_readlane_b32 s5, v252, 3
	s_cmp_lt_i32 s2, s5
	s_cselect_b64 s[4:5], -1, 0
	s_and_b64 s[0:1], s[0:1], s[4:5]
	s_andn2_b64 vcc, exec, s[0:1]
	s_cbranch_vccnz .LBB0_1631
	s_waitcnt vmcnt(0)
	v_readlane_b32 s0, v252, 18
	v_readlane_b32 s1, v252, 19
	s_andn2_b64 vcc, exec, s[0:1]
	s_barrier
	v_readlane_b32 s100, v252, 6
	s_nop 0
	s_cmp_lg_u32 s100, 1
	s_cbranch_scc1 .Lmy_inv_skip4
	buffer_inv sc1
.Lmy_inv_skip4:
	s_cbranch_vccnz .LBB0_1630
	v_mbcnt_lo_u32_b32 v0, -1, 0
	v_mbcnt_hi_u32_b32 v0, -1, v0
	s_nop 0
	v_cmp_eq_u32_e32 vcc, 0, v0
	s_and_saveexec_b64 s[0:1], vcc
	s_cbranch_execz .LBB0_1629
	v_readlane_b32 s6, v255, 0
	s_waitcnt vmcnt(0) expcnt(0) lgkmcnt(0)
	s_nop 0
	v_mov_b32_e32 v0, s6
	ds_read_b32 v2, v0
	v_readlane_b32 s6, v255, 1
	s_waitcnt lgkmcnt(0)
	v_cmp_ne_u32_e32 vcc, 0, v2
	v_mov_b32_e32 v0, s6
	ds_read_b32 v0, v0
	s_cbranch_vccnz .LBB0_1595
	v_readlane_b32 s8, v252, 8
	v_readlane_b32 s9, v252, 9
	s_load_dwordx2 s[6:7], s[8:9], 0x0
	s_nop 0
	s_load_dword s8, s[8:9], 0x8
	s_mov_b32 s13, 1
	s_waitcnt lgkmcnt(0)
	s_mul_i32 s12, s7, s6
	s_mul_i32 s12, s12, s8
	s_branch .LBB0_1583

.LBB0_1662:
	v_readlane_b32 s2, v255, 9
	v_readlane_b32 s4, v252, 2
	s_add_i32 s2, s2, 7
	v_readlane_b32 s5, v252, 3
	s_cmp_lt_i32 s2, s5
	s_cselect_b64 s[4:5], -1, 0
	s_and_b64 s[0:1], s[0:1], s[4:5]
	s_andn2_b64 vcc, exec, s[0:1]
	s_cbranch_vccnz .LBB0_1716
	s_waitcnt vmcnt(0)
	v_readlane_b32 s0, v252, 18
	v_readlane_b32 s1, v252, 19
	s_andn2_b64 vcc, exec, s[0:1]
	s_barrier
	v_readlane_b32 s100, v252, 6
	s_nop 0
	s_cmp_lg_u32 s100, 1
	s_cbranch_scc1 .Lmy_inv_skip5
	buffer_inv sc1

.LBB0_1769:
	v_readlane_b32 s0, v255, 9
	s_add_i32 s20, s0, 8
	v_readlane_b32 s0, v252, 2
	v_readlane_b32 s1, v252, 3
	s_cmp_ge_i32 s20, s1
	s_cbranch_scc1 .LBB0_1823
	s_waitcnt vmcnt(0)
	v_readlane_b32 s0, v252, 18
	v_readlane_b32 s1, v252, 19
	s_andn2_b64 vcc, exec, s[0:1]
	s_waitcnt lgkmcnt(0)
	s_barrier
	v_readlane_b32 s100, v252, 6
	s_nop 0
	s_cmp_lg_u32 s100, 1
	s_cbranch_scc1 .Lmy_inv_skip6
	buffer_inv sc1

.LBB0_1789:
	s_or_b64 exec, exec, s[6:7]
	v_cvt_f32_u32_e32 v5, v2
	s_waitcnt vmcnt(0)
	v_readfirstlane_b32 s6, v4
	v_sub_u32_e32 v4, 0, v2
	v_rcp_iflag_f32_e32 v5, v5
	v_add_u32_e32 v6, s6, v1
	v_mul_f32_e32 v5, 0x4f7ffffe, v5
	v_cvt_u32_f32_e32 v5, v5
	v_mul_lo_u32 v1, v4, v5
	v_mul_hi_u32 v1, v5, v1
	v_add_u32_e32 v1, v5, v1
	v_mul_hi_u32 v1, v6, v1
	v_mul_lo_u32 v4, v1, v2
	v_sub_u32_e32 v4, v6, v4
	v_add_u32_e32 v5, 1, v1
	v_cmp_ge_u32_e32 vcc, v4, v2
	s_nop 1
	v_cndmask_b32_e32 v1, v1, v5, vcc
	v_sub_u32_e32 v5, v4, v2
	v_cndmask_b32_e32 v4, v4, v5, vcc
	v_add_u32_e32 v5, 1, v1
	v_cmp_ge_u32_e32 vcc, v4, v2
	v_add_u32_e32 v4, 1, v6
	s_nop 0
	v_cndmask_b32_e32 v1, v1, v5, vcc
	v_mul_lo_u32 v5, v2, v1
	v_add_u32_e32 v2, v5, v2
	v_cmp_ne_u32_e32 vcc, v4, v2
	s_and_saveexec_b64 s[6:7], vcc
	s_xor_b64 s[6:7], exec, s[6:7]
	s_cbranch_execz .LBB0_1803
	v_readlane_b32 s8, v253, 26
	v_readlane_b32 s9, v253, 27
	s_waitcnt lgkmcnt(0)
	v_add_u32_e32 v1, 1, v1
	v_mul_lo_u32 v1, v1, v0
	s_nop 2
	global_load_dword v0, v3, s[8:9] sc1
	s_waitcnt vmcnt(0)
	v_cmp_lt_u32_e32 vcc, v0, v1
	s_and_saveexec_b64 s[8:9], vcc
	s_cbranch_execz .LBB0_1802
	s_mov_b32 s21, 1
	s_mov_b64 s[10:11], 0
	s_branch .LBB0_1793

.LBB0_1925:
	v_readlane_b32 s2, v255, 9
	v_readlane_b32 s4, v252, 2
	s_add_i32 s2, s2, 9
	v_readlane_b32 s5, v252, 3
	s_cmp_lt_i32 s2, s5
	s_cselect_b64 s[4:5], -1, 0
	s_and_b64 s[0:1], s[0:1], s[4:5]
	s_andn2_b64 vcc, exec, s[0:1]
	s_cbranch_vccnz .LBB0_1979
	s_waitcnt vmcnt(0)
	v_readlane_b32 s0, v252, 18
	v_readlane_b32 s1, v252, 19
	s_andn2_b64 vcc, exec, s[0:1]
	s_waitcnt lgkmcnt(0)
	s_barrier
	v_readlane_b32 s100, v252, 6
	s_nop 0
	s_cmp_lg_u32 s100, 1
	s_cbranch_scc1 .Lmy_inv_skip7
	buffer_inv sc1
.Lmy_inv_skip7:
	s_cbranch_vccnz .LBB0_1978
	v_mbcnt_lo_u32_b32 v0, -1, 0
	v_mbcnt_hi_u32_b32 v0, -1, v0
	s_nop 0
	v_cmp_eq_u32_e32 vcc, 0, v0
	s_and_saveexec_b64 s[0:1], vcc
	s_cbranch_execz .LBB0_1977
	v_readlane_b32 s6, v255, 0
	s_waitcnt vmcnt(0) expcnt(0) lgkmcnt(0)
	s_nop 0
	v_mov_b32_e32 v0, s6
	ds_read_b32 v2, v0
	v_readlane_b32 s6, v255, 1
	s_waitcnt lgkmcnt(0)
	v_cmp_ne_u32_e32 vcc, 0, v2
	v_mov_b32_e32 v0, s6
	ds_read_b32 v0, v0
	s_cbranch_vccnz .LBB0_1943
	v_readlane_b32 s10, v252, 8
	v_readlane_b32 s11, v252, 9
	s_load_dwordx2 s[6:7], s[10:11], 0x0
	s_nop 0
	s_load_dword s10, s[10:11], 0x8
	s_mov_b32 s15, 1
	s_waitcnt lgkmcnt(0)
	s_mul_i32 s14, s7, s6
	s_mul_i32 s14, s14, s10
	s_branch .LBB0_1931

.LBB0_1945:
	s_or_b64 exec, exec, s[6:7]
	v_cvt_f32_u32_e32 v5, v2
	s_waitcnt vmcnt(0)
	v_readfirstlane_b32 s6, v4
	v_sub_u32_e32 v4, 0, v2
	v_rcp_iflag_f32_e32 v5, v5
	v_add_u32_e32 v6, s6, v1
	v_mul_f32_e32 v5, 0x4f7ffffe, v5
	v_cvt_u32_f32_e32 v5, v5
	v_mul_lo_u32 v1, v4, v5
	v_mul_hi_u32 v1, v5, v1
	v_add_u32_e32 v1, v5, v1
	v_mul_hi_u32 v1, v6, v1
	v_mul_lo_u32 v4, v1, v2
	v_sub_u32_e32 v4, v6, v4
	v_add_u32_e32 v5, 1, v1
	v_cmp_ge_u32_e32 vcc, v4, v2
	s_nop 1
	v_cndmask_b32_e32 v1, v1, v5, vcc
	v_sub_u32_e32 v5, v4, v2
	v_cndmask_b32_e32 v4, v4, v5, vcc
	v_add_u32_e32 v5, 1, v1
	v_cmp_ge_u32_e32 vcc, v4, v2
	v_add_u32_e32 v4, 1, v6
	s_nop 0
	v_cndmask_b32_e32 v1, v1, v5, vcc
	v_mul_lo_u32 v5, v2, v1
	v_add_u32_e32 v2, v5, v2
	v_cmp_ne_u32_e32 vcc, v4, v2
	s_and_saveexec_b64 s[6:7], vcc
	s_xor_b64 s[6:7], exec, s[6:7]
	s_cbranch_execz .LBB0_1959
	v_readlane_b32 s10, v253, 26
	v_readlane_b32 s11, v253, 27
	s_waitcnt lgkmcnt(0)
	v_add_u32_e32 v1, 1, v1
	v_mul_lo_u32 v1, v1, v0
	s_nop 2
	global_load_dword v0, v3, s[10:11] sc1
	s_waitcnt vmcnt(0)
	v_cmp_lt_u32_e32 vcc, v0, v1
	s_and_saveexec_b64 s[10:11], vcc
	s_cbranch_execz .LBB0_1958
	s_mov_b32 s22, 1
	s_mov_b64 s[12:13], 0
	s_branch .LBB0_1949

.LBB0_1959:
	s_andn2_saveexec_b64 s[6:7], s[6:7]
	s_cbranch_execz .LBB0_1977
	s_mov_b64 s[6:7], exec
	buffer_wbl2 sc1
	s_waitcnt vmcnt(0) lgkmcnt(0)
	s_waitcnt vmcnt(0)
	v_mbcnt_lo_u32_b32 v1, s6, 0
	v_mbcnt_hi_u32_b32 v1, s7, v1
	v_cmp_eq_u32_e32 vcc, 0, v1
	s_and_saveexec_b64 s[10:11], vcc
	s_cbranch_execz .LBB0_1962
	s_bcnt1_i32_b64 s6, s[6:7]
	v_mov_b32_e32 v2, s6
	v_readlane_b32 s6, v253, 26
	v_readlane_b32 s7, v253, 27
	s_nop 4
	global_atomic_add v2, v3, v2, s[6:7] sc0

.LBB0_2035:
	s_waitcnt vmcnt(0)
	v_readlane_b32 s0, v252, 18
	v_readlane_b32 s1, v252, 19
	s_andn2_b64 vcc, exec, s[0:1]
	s_waitcnt lgkmcnt(0)
	s_barrier
	v_readlane_b32 s100, v252, 6
	s_nop 0
	s_cmp_lg_u32 s100, 1
	s_cbranch_scc1 .Lmy_inv_skip8
	buffer_inv sc1
.Lmy_inv_skip8:
	s_cbranch_vccz .LBB0_2036
	s_getpc_b64 s[98:99]

.LBB0_2054:
	s_or_b64 exec, exec, s[4:5]
	v_cvt_f32_u32_e32 v5, v2
	s_waitcnt vmcnt(0)
	v_readfirstlane_b32 s2, v4
	v_sub_u32_e32 v4, 0, v2
	v_rcp_iflag_f32_e32 v5, v5
	v_add_u32_e32 v6, s2, v1
	v_mul_f32_e32 v5, 0x4f7ffffe, v5
	v_cvt_u32_f32_e32 v5, v5
	v_mul_lo_u32 v1, v4, v5
	v_mul_hi_u32 v1, v5, v1
	v_add_u32_e32 v1, v5, v1
	v_mul_hi_u32 v1, v6, v1
	v_mul_lo_u32 v4, v1, v2
	v_sub_u32_e32 v4, v6, v4
	v_add_u32_e32 v5, 1, v1
	v_cmp_ge_u32_e32 vcc, v4, v2
	s_nop 1
	v_cndmask_b32_e32 v1, v1, v5, vcc
	v_sub_u32_e32 v5, v4, v2
	v_cndmask_b32_e32 v4, v4, v5, vcc
	v_add_u32_e32 v5, 1, v1
	v_cmp_ge_u32_e32 vcc, v4, v2
	v_add_u32_e32 v4, 1, v6
	s_nop 0
	v_cndmask_b32_e32 v1, v1, v5, vcc
	v_mul_lo_u32 v5, v2, v1
	v_add_u32_e32 v2, v5, v2
	v_cmp_ne_u32_e32 vcc, v4, v2
	s_and_saveexec_b64 s[4:5], vcc
	s_xor_b64 s[4:5], exec, s[4:5]
	s_cbranch_execz .LBB0_2068
	v_readlane_b32 s6, v253, 26
	v_readlane_b32 s7, v253, 27
	s_waitcnt lgkmcnt(0)
	v_add_u32_e32 v1, 1, v1
	v_mul_lo_u32 v1, v1, v0
	s_nop 2
	global_load_dword v0, v3, s[6:7] sc1
	s_waitcnt vmcnt(0)
	v_cmp_lt_u32_e32 vcc, v0, v1
	s_and_saveexec_b64 s[6:7], vcc
	s_cbranch_execz .LBB0_2067
	s_mov_b32 s2, 1
	s_mov_b64 s[10:11], 0
	s_branch .LBB0_2058

.LBB0_2069:
	s_mov_b64 s[4:5], exec
	buffer_wbl2 sc1
	s_waitcnt vmcnt(0) lgkmcnt(0)
	s_waitcnt vmcnt(0)
	v_mbcnt_lo_u32_b32 v1, s4, 0
	v_mbcnt_hi_u32_b32 v1, s5, v1
	v_cmp_eq_u32_e32 vcc, 0, v1
	s_and_saveexec_b64 s[6:7], vcc
	s_cbranch_execz .LBB0_2071
	s_bcnt1_i32_b64 s2, s[4:5]
	v_readlane_b32 s4, v253, 26
	v_mov_b32_e32 v2, s2
	v_readlane_b32 s5, v253, 27
	s_nop 4
	global_atomic_add v2, v3, v2, s[4:5] sc0
